# GEMM: first K-trip of every unit peeled (first MFMA per accumulator takes C=0): the 128-register accumulator zeroing at phase starts and unit boundaries removed
# baseline (speedup 1.0000x reference)
.LBB0_116:
	s_lshl_b32 s69, s13, 6
	v_add_u32_e32 v1, s69, v0
	v_ashrrev_i32_e32 v3, 31, v1
	v_lshrrev_b32_e32 v3, 26, v3
	v_lshlrev_b32_e32 v2, 4, v1
	v_add_u32_e32 v3, v1, v3
	v_bfe_i32 v1, v1, 27, 1
	v_lshrrev_b32_e32 v1, 22, v1
	v_add_u32_e32 v1, v2, v1
	v_and_b32_e32 v1, 0xfffffc00, v1
	v_sub_u32_e32 v1, v2, v1
	v_lshrrev_b32_e32 v4, 4, v1
	v_bitop3_b32 v1, v4, v1, 32 bitop3:0x6c
	v_ashrrev_i32_e32 v5, 31, v1
	v_lshrrev_b32_e32 v5, 26, v5
	v_add_u32_e32 v5, v1, v5
	v_ashrrev_i32_e32 v6, 6, v5
	v_and_b32_e32 v5, 0xc0, v5
	v_ashrrev_i32_e32 v3, 6, v3
	v_sub_u32_e32 v1, v1, v5
	v_lshlrev_b32_e32 v4, 3, v3
	v_lshlrev_b32_e32 v3, 5, v3
	v_ashrrev_i16_sdwa v1, v246, sext(v1) dst_sel:DWORD dst_unused:UNUSED_PAD src0_sel:DWORD src1_sel:BYTE_0
	v_and_b32_e32 v3, 32, v3
	v_bfe_i32 v1, v1, 0, 16
	v_add_lshl_u32 v182, v3, v1, 1
	v_add_u32_e32 v1, 0x2000, v2
	v_ashrrev_i32_e32 v2, 31, v1
	v_lshrrev_b32_e32 v2, 22, v2
	v_add_u32_e32 v2, v1, v2
	v_ashrrev_i32_e32 v2, 10, v2
	v_and_b32_e32 v4, -16, v4
	v_mul_i32_i24_e32 v3, 0x400, v2
	v_add_u32_e32 v4, v6, v4
	v_sub_u32_e32 v1, v1, v3
	v_lshlrev_b32_e32 v183, 1, v4
	v_lshrrev_b32_e32 v7, 2, v4
	v_and_b32_e32 v6, 3, v6
	s_mov_b32 s2, 0x7fffffe0
	v_lshrrev_b32_e32 v3, 4, v1
	v_and_b32_e32 v5, 24, v183
	v_and_b32_e32 v7, 4, v7
	v_and_or_b32 v6, v4, s2, v6
	v_bitop3_b32 v1, v3, v1, 32 bitop3:0x6c
	v_or3_b32 v5, v6, v7, v5
	v_ashrrev_i32_e32 v6, 31, v1
	v_lshrrev_b32_e32 v6, 26, v6
	v_lshlrev_b32_e32 v3, 3, v2
	v_add_u32_e32 v6, v1, v6
	v_and_b32_e32 v3, -16, v3
	v_ashrrev_i32_e32 v7, 6, v6
	v_and_b32_e32 v6, 0xc0, v6
	v_add_u32_e32 v3, v7, v3
	v_sub_u32_e32 v1, v1, v6
	v_lshlrev_b32_e32 v2, 5, v2
	v_ashrrev_i16_sdwa v1, v246, sext(v1) dst_sel:DWORD dst_unused:UNUSED_PAD src0_sel:DWORD src1_sel:BYTE_0
	v_lshlrev_b32_e32 v248, 1, v3
	v_lshrrev_b32_e32 v8, 2, v3
	v_and_b32_e32 v7, 3, v7
	v_and_b32_e32 v2, 32, v2
	v_bfe_i32 v1, v1, 0, 16
	v_and_b32_e32 v6, 24, v248
	v_and_b32_e32 v8, 4, v8
	v_and_or_b32 v7, v3, s2, v7
	v_or3_b32 v6, v7, v8, v6
	v_add_lshl_u32 v184, v2, v1, 1
	v_and_b32_e32 v1, 48, v0
	v_lshlrev_b32_e32 v8, 6, v0
	s_movk_i32 s2, 0x3c0
	v_and_or_b32 v1, v8, s2, v1
	s_mul_i32 s2, s45, 0xc00
	s_and_b32 s8, s13, 3
	s_ashr_i32 s6, s13, 2
	s_ashr_i32 s3, s2, 31
	s_lshl_b32 s20, s13, 10
	s_lshl_b32 s9, s6, 6
	s_lshl_b32 s7, s8, 5
	s_lshl_b64 s[2:3], s[2:3], 2
	s_waitcnt lgkmcnt(0)
	s_add_u32 s2, s4, s2
	s_addc_u32 s3, s5, s3
	s_add_u32 s2, s2, 0x20000
	s_addc_u32 s3, s3, 0
	v_writelane_b32 v254, s2, 60
	s_ashr_i32 s11, s10, 31
	v_writelane_b32 v255, s45, 5
	v_writelane_b32 v254, s3, 61
	s_mov_b32 s2, s10
	v_writelane_b32 v254, s2, 36
	v_lshlrev_b32_e32 v2, 4, v0
	v_and_b32_e32 v2, 0xfffffc00, v2
	v_writelane_b32 v254, s3, 37
	s_lshl_b64 s[2:3], s[10:11], 19
	s_add_u32 s54, s30, s2
	s_addc_u32 s55, s31, s3
	s_ashr_i32 s75, s74, 31
	s_lshl_b64 s[2:3], s[74:75], 19
	s_add_u32 s60, s52, s2
	s_addc_u32 s61, s53, s3
	s_cmpk_lt_i32 s86, 0x50
	s_cselect_b64 s[2:3], -1, 0
	v_writelane_b32 v254, s2, 47
	v_lshlrev_b32_e32 v0, 2, v0
	s_mul_i32 s10, s14, 6
	v_writelane_b32 v254, s3, 48
	s_and_b64 s[2:3], s[2:3], exec
	s_cselect_b32 s21, 2, 1
	s_add_i32 s2, s86, 0x100
	v_writelane_b32 v254, s2, 58
	s_lshr_b32 s2, s90, 3
	s_and_b32 s75, s90, 7
	v_writelane_b32 v254, s2, 51
	s_add_i32 s2, s2, 1
	v_writelane_b32 v254, s2, 52
	s_mul_i32 s2, s2, s75
	v_writelane_b32 v254, s2, 59
	s_mul_i32 s2, s58, 48
	s_sub_i32 s2, s2, 48
	v_writelane_b32 v255, s2, 6
	s_mov_b32 s2, s58
	v_writelane_b32 v255, s2, 7
	s_ashr_i32 s87, s86, 31
	v_writelane_b32 v254, s14, 42
	v_writelane_b32 v255, s3, 8
	s_lshl_b32 s2, s58, 6
	s_mov_b32 s3, s15
	v_writelane_b32 v255, s2, 9
	s_cmp_eq_u32 s6, 1
	v_lshl_add_u32 v7, s6, 13, v2
	v_writelane_b32 v255, s3, 10
	s_mul_i32 s2, s16, 48
	v_writelane_b32 v254, s2, 46
	s_cselect_b64 s[2:3], -1, 0
	v_writelane_b32 v254, s2, 56
	v_and_b32_e32 v0, 32, v0
	v_lshl_add_u32 v2, s8, 12, v2
	v_writelane_b32 v254, s3, 57
	s_mul_i32 s2, s17, 0x120000
	s_mul_hi_u32 s3, s16, 0x120000
	s_add_i32 s2, s3, s2
	v_writelane_b32 v255, s2, 11
	s_mul_i32 s2, s17, 0x700000
	s_mul_hi_u32 s3, s16, 0x700000
	s_add_i32 s2, s3, s2
	v_writelane_b32 v255, s2, 12
	s_mul_i32 s2, s16, 0x700000
	v_writelane_b32 v255, s2, 13
	s_lshl_b64 s[2:3], s[16:17], 20
	v_writelane_b32 v255, s2, 14
	s_cmp_lt_u32 s13, 4
	v_bitop3_b32 v7, v1, v7, v0 bitop3:0xde
	v_writelane_b32 v255, s3, 15
	s_cselect_b64 s[2:3], -1, 0
	v_writelane_b32 v254, s2, 38
	s_lshl_b32 s11, s8, 6
	v_writelane_b32 v255, s13, 16
	v_writelane_b32 v254, s3, 39
	s_add_i32 s2, s16, -1
	s_cmp_eq_u32 s16, 1
	s_cselect_b64 s[4:5], -1, 0
	v_writelane_b32 v255, s4, 17
	s_add_i32 s3, s9, 0x80
	v_bitop3_b32 v250, v1, v2, v0 bitop3:0xde
	v_writelane_b32 v255, s5, 18
	v_writelane_b32 v255, s3, 19
	v_writelane_b32 v255, s6, 20
	s_lshl_b32 s3, s6, 9
	v_writelane_b32 v255, s3, 21
	s_mul_i32 s3, s17, 0xe0000
	v_writelane_b32 v255, s16, 22
	s_mul_hi_u32 s4, s16, 0xe0000
	s_add_i32 s3, s4, s3
	s_cmp_eq_u32 s8, 0
	s_cselect_b64 s[4:5], -1, 0
	s_abs_i32 s26, s10
	v_cvt_f32_u32_e32 v0, s26
	v_writelane_b32 v255, s17, 23
	v_writelane_b32 v255, s3, 24
	v_writelane_b32 v255, s8, 25
	v_rcp_iflag_f32_e32 v0, v0
	v_writelane_b32 v255, s4, 26
	v_lshl_add_u32 v188, v4, 11, v182
	v_mov_b32_e32 v4, 0
	v_mul_f32_e32 v0, 0x4f7ffffe, v0
	v_writelane_b32 v255, s5, 27
	s_mul_hi_i32 s5, s2, 0x380000
	s_mul_i32 s4, s2, 0x380000
	s_or_b32 s2, s11, 32
	v_cvt_u32_f32_e32 v0, v0
	v_writelane_b32 v255, s2, 28
	v_writelane_b32 v255, s7, 29
	s_or_b32 s2, s7, 0x80
	v_writelane_b32 v255, s2, 30
	s_add_i32 s2, s38, 0xffffff40
	v_writelane_b32 v255, s2, 31
	s_sub_i32 s2, 0, s26
	v_readfirstlane_b32 s3, v0
	s_mul_i32 s2, s2, s3
	s_lshl_b64 s[4:5], s[4:5], 1
	s_mul_hi_u32 s2, s3, s2
	v_writelane_b32 v255, s4, 32
	v_lshlrev_b32_e32 v185, 1, v5
	s_movk_i32 s56, 0x400
	v_lshlrev_b32_e32 v249, 1, v6
	v_lshl_add_u32 v192, v5, 11, v182
	v_lshl_add_u32 v186, v3, 11, v184
	v_lshl_add_u32 v190, v6, 11, v184
	s_mov_b32 s91, s15
	v_writelane_b32 v254, s9, 45
	s_mov_b32 s62, 0
	s_mov_b32 s19, s11
	s_mov_b32 s18, s10
	s_ashr_i32 s77, s10, 31
	s_add_i32 s93, s3, s2
	s_mov_b32 s3, 16
	s_mov_b64 s[44:45], 0x40000
	s_mov_b32 s2, 8
	s_mov_b64 s[16:17], -1
	v_add_u32_e32 v240, 0, v7
	v_writelane_b32 v255, s5, 33
	s_mov_b32 s76, s39
.LBB0_117:
	s_mov_b64 s[8:9], -1
	s_mov_b64 s[4:5], 0
	s_cmp_lt_i32 s39, 2
	s_mov_b64 s[6:7], 0
	s_cbranch_scc1 .LBB0_128
	s_cmp_gt_i32 s39, 3
	s_cbranch_scc0 .LBB0_120
	s_cmp_lg_u32 s39, 4
	s_mov_b64 s[8:9], 0
	s_cselect_b64 s[6:7], -1, 0

.LBB0_287:
	s_waitcnt lgkmcnt(0)
	v_mad_u64_u32 v[196:197], s[6:7], s14, v183, v[182:183]
	v_mad_u64_u32 v[194:195], s[6:7], v185, s14, v[182:183]
	v_mad_u64_u32 v[200:201], s[6:7], s14, v248, v[184:185]
	v_mad_u64_u32 v[198:199], s[6:7], v249, s14, v[184:185]
	s_sub_i32 s6, s94, 32
	s_mul_hi_u32 s7, s6, 0xaaaaaaab
	s_lshr_b32 s7, s7, 2
	s_mul_i32 s7, s7, 6
	s_sub_i32 s6, s6, s7
	s_cmp_gt_u32 s6, 1
	s_cselect_b32 s6, 1, 3
	s_cmp_gt_i32 s94, 31
	s_cselect_b32 s72, s6, 1
	s_add_u32 s6, s44, 0x80
	v_mov_b32_e32 v189, v113
	v_mov_b32_e32 v187, v113
	s_addc_u32 s7, s45, 0
	s_mov_b32 s33, 2
	v_lshl_add_u64 v[130:131], s[6:7], 0, v[188:189]
	v_lshl_add_u64 v[132:133], s[6:7], 0, v[186:187]
	s_mov_b64 s[22:23], 0x100
	s_mov_b64 s[24:25], 0
	s_mov_b64 s[6:7], 0
	s_branch .Lk1_body

.Lk1_body:
	s_add_u32 s48, s54, s22
	s_addc_u32 s49, s55, s23
	s_and_b64 s[34:35], s[6:7], exec
	s_cselect_b32 s36, s40, s60
	s_cselect_b32 s37, s41, s61
	s_add_u32 s50, s60, s22
	s_addc_u32 s51, s61, s23
	s_and_b64 s[34:35], s[24:25], exec
	s_cselect_b32 s35, s37, s51
	s_cselect_b32 s34, s36, s50
	s_and_b64 s[36:37], s[6:7], exec
	s_cselect_b32 s36, s28, s54
	s_cselect_b32 s37, s29, s55
	s_and_b64 s[24:25], s[24:25], exec
	s_cselect_b32 s25, s37, s49
	s_cselect_b32 s24, s36, s48
	s_add_i32 s37, 0, 0x10000
	v_add_u32_e32 v112, s37, v250
	s_add_i32 s48, 0, 0x14000
	ds_read_b128 v[134:137], v112
	ds_read_b128 v[138:141], v112 offset:1024
	ds_read_b128 v[142:145], v112 offset:2048
	ds_read_b128 v[146:149], v112 offset:3072
	v_add_u32_e32 v112, s48, v250
	ds_read_b128 v[150:153], v112
	ds_read_b128 v[154:157], v112 offset:1024
	ds_read_b128 v[158:161], v112 offset:2048
	ds_read_b128 v[162:165], v112 offset:3072
	v_cndmask_b32_e64 v214, v188, v196, s[6:7]
	v_cndmask_b32_e64 v112, v192, v194, s[6:7]
	v_cndmask_b32_e64 v216, v186, v200, s[6:7]
	v_cndmask_b32_e64 v222, v190, v198, s[6:7]
	s_add_i32 s36, s20, 0
	v_lshl_add_u64 v[224:225], s[54:55], 0, v[130:131]
	s_add_i32 m0, s36, 0xc000
	ds_read_b128 v[166:169], v240
	ds_read_b128 v[170:173], v240 offset:1024
	ds_read_b128 v[174:177], v240 offset:2048
	ds_read_b128 v[178:181], v240 offset:3072
	ds_read_b128 v[202:205], v240 offset:4096
	ds_read_b128 v[206:209], v240 offset:5120
	ds_read_b128 v[210:213], v240 offset:6144
	ds_read_b128 v[218:221], v240 offset:7168
	global_load_lds_dwordx4 v[224:225], off
	v_lshl_add_u64 v[224:225], s[54:55], 0, v[132:133]
	s_add_i32 m0, s36, 0xe000
	s_nop 0
	global_load_lds_dwordx4 v[224:225], off
	s_waitcnt vmcnt(8)
	s_waitcnt lgkmcnt(0)
	s_barrier
	s_setprio 1
	s_waitcnt lgkmcnt(0)
	v_mfma_f32_16x16x32_bf16 v[126:129], v[134:137], v[166:169], 0
	v_mfma_f32_16x16x32_bf16 v[122:125], v[142:145], v[166:169], 0
	v_mfma_f32_16x16x32_bf16 v[108:111], v[134:137], v[174:177], 0
	v_mfma_f32_16x16x32_bf16 v[104:107], v[142:145], v[174:177], 0
	v_mfma_f32_16x16x32_bf16 v[92:95], v[134:137], v[202:205], 0
	v_mfma_f32_16x16x32_bf16 v[88:91], v[142:145], v[202:205], 0
	v_mfma_f32_16x16x32_bf16 v[76:79], v[134:137], v[210:213], 0
	v_mfma_f32_16x16x32_bf16 v[72:75], v[142:145], v[210:213], 0
	v_mfma_f32_16x16x32_bf16 v[126:129], v[138:141], v[170:173], v[126:129]
	v_mfma_f32_16x16x32_bf16 v[122:125], v[146:149], v[170:173], v[122:125]
	v_mfma_f32_16x16x32_bf16 v[108:111], v[138:141], v[178:181], v[108:111]
	v_mfma_f32_16x16x32_bf16 v[104:107], v[146:149], v[178:181], v[104:107]
	v_mfma_f32_16x16x32_bf16 v[92:95], v[138:141], v[206:209], v[92:95]
	v_mfma_f32_16x16x32_bf16 v[88:91], v[146:149], v[206:209], v[88:91]
	v_mfma_f32_16x16x32_bf16 v[76:79], v[138:141], v[218:221], v[76:79]
	v_mfma_f32_16x16x32_bf16 v[72:75], v[146:149], v[218:221], v[72:75]
	s_setprio 0
	s_setprio 1
	v_mfma_f32_16x16x32_bf16 v[118:121], v[150:153], v[166:169], 0
	v_mfma_f32_16x16x32_bf16 v[114:117], v[158:161], v[166:169], 0
	v_mfma_f32_16x16x32_bf16 v[100:103], v[150:153], v[174:177], 0
	v_mfma_f32_16x16x32_bf16 v[96:99], v[158:161], v[174:177], 0
	v_mfma_f32_16x16x32_bf16 v[84:87], v[150:153], v[202:205], 0
	v_mfma_f32_16x16x32_bf16 v[80:83], v[158:161], v[202:205], 0
	v_mfma_f32_16x16x32_bf16 v[68:71], v[150:153], v[210:213], 0
	v_mfma_f32_16x16x32_bf16 v[64:67], v[158:161], v[210:213], 0
	v_mfma_f32_16x16x32_bf16 v[118:121], v[154:157], v[170:173], v[118:121]
	v_mfma_f32_16x16x32_bf16 v[114:117], v[162:165], v[170:173], v[114:117]
	v_mfma_f32_16x16x32_bf16 v[100:103], v[154:157], v[178:181], v[100:103]
	v_mfma_f32_16x16x32_bf16 v[96:99], v[162:165], v[178:181], v[96:99]
	v_mfma_f32_16x16x32_bf16 v[84:87], v[154:157], v[206:209], v[84:87]
	v_mfma_f32_16x16x32_bf16 v[80:83], v[162:165], v[206:209], v[80:83]
	v_mfma_f32_16x16x32_bf16 v[68:71], v[154:157], v[218:221], v[68:71]
	v_mfma_f32_16x16x32_bf16 v[64:67], v[162:165], v[218:221], v[64:67]
	s_setprio 0
	s_barrier
	s_add_i32 s37, s37, s20
	s_mov_b32 m0, s37
	ds_read_b128 v[166:169], v240 offset:16384
	ds_read_b128 v[170:173], v240 offset:17408
	ds_read_b128 v[174:177], v240 offset:18432
	ds_read_b128 v[178:181], v240 offset:19456
	ds_read_b128 v[202:205], v240 offset:20480
	ds_read_b128 v[206:209], v240 offset:21504
	ds_read_b128 v[210:213], v240 offset:22528
	ds_read_b128 v[218:221], v240 offset:23552
	global_load_lds_dwordx4 v112, s[34:35]
	s_add_i32 m0, s37, 0x2000
	s_and_b64 s[6:7], s[6:7], exec
	s_cselect_b32 s49, s64, s44
	v_mov_b32_e32 v223, v113
	s_cselect_b32 s37, s65, s45
	s_add_u32 s6, s34, s49
	v_lshl_add_u64 v[224:225], s[34:35], 0, v[112:113]
	v_lshl_add_u64 v[226:227], s[34:35], 0, v[222:223]
	global_load_lds_dwordx4 v222, s[34:35]
	s_addc_u32 s7, s35, s37
	s_add_i32 s34, s48, s20
	s_mov_b32 m0, s34
	v_mov_b32_e32 v215, v113
	global_load_lds_dwordx4 v112, s[6:7]
	s_add_i32 m0, s34, 0x2000
	v_mov_b32_e32 v217, v113
	global_load_lds_dwordx4 v222, s[6:7]
	s_mov_b32 m0, s36
	v_lshl_add_u64 v[228:229], s[6:7], 0, v[112:113]
	global_load_lds_dwordx4 v214, s[24:25]
	s_add_i32 m0, s36, 0x2000
	v_lshl_add_u64 v[230:231], s[6:7], 0, v[222:223]
	global_load_lds_dwordx4 v216, s[24:25]
	s_waitcnt vmcnt(8)
	s_waitcnt lgkmcnt(0)
	v_lshl_add_u64 v[222:223], s[24:25], 0, v[214:215]
	v_lshl_add_u64 v[232:233], s[24:25], 0, v[216:217]
	s_barrier
	s_setprio 1
	s_waitcnt lgkmcnt(0)
	v_mfma_f32_16x16x32_bf16 v[60:63], v[134:137], v[166:169], 0
	v_mfma_f32_16x16x32_bf16 v[56:59], v[142:145], v[166:169], 0
	v_mfma_f32_16x16x32_bf16 v[44:47], v[134:137], v[174:177], 0
	v_mfma_f32_16x16x32_bf16 v[40:43], v[142:145], v[174:177], 0
	v_mfma_f32_16x16x32_bf16 v[28:31], v[134:137], v[202:205], 0
	v_mfma_f32_16x16x32_bf16 v[24:27], v[142:145], v[202:205], 0
	v_mfma_f32_16x16x32_bf16 v[12:15], v[134:137], v[210:213], 0
	v_mfma_f32_16x16x32_bf16 v[4:7], v[142:145], v[210:213], 0
	v_mfma_f32_16x16x32_bf16 v[60:63], v[138:141], v[170:173], v[60:63]
	v_mfma_f32_16x16x32_bf16 v[56:59], v[146:149], v[170:173], v[56:59]
	v_mfma_f32_16x16x32_bf16 v[44:47], v[138:141], v[178:181], v[44:47]
	v_mfma_f32_16x16x32_bf16 v[40:43], v[146:149], v[178:181], v[40:43]
	v_mfma_f32_16x16x32_bf16 v[28:31], v[138:141], v[206:209], v[28:31]
	v_mfma_f32_16x16x32_bf16 v[24:27], v[146:149], v[206:209], v[24:27]
	v_mfma_f32_16x16x32_bf16 v[12:15], v[138:141], v[218:221], v[12:15]
	v_mfma_f32_16x16x32_bf16 v[4:7], v[146:149], v[218:221], v[4:7]
	s_setprio 0
	s_setprio 1
	v_mfma_f32_16x16x32_bf16 v[52:55], v[150:153], v[166:169], 0
	v_mfma_f32_16x16x32_bf16 v[48:51], v[158:161], v[166:169], 0
	v_mfma_f32_16x16x32_bf16 v[36:39], v[150:153], v[174:177], 0
	v_mfma_f32_16x16x32_bf16 v[32:35], v[158:161], v[174:177], 0
	v_mfma_f32_16x16x32_bf16 v[20:23], v[150:153], v[202:205], 0
	v_mfma_f32_16x16x32_bf16 v[16:19], v[158:161], v[202:205], 0
	v_mfma_f32_16x16x32_bf16 v[8:11], v[150:153], v[210:213], 0
	v_mfma_f32_16x16x32_bf16 v[0:3], v[158:161], v[210:213], 0
	v_mfma_f32_16x16x32_bf16 v[52:55], v[154:157], v[170:173], v[52:55]
	v_mfma_f32_16x16x32_bf16 v[48:51], v[162:165], v[170:173], v[48:51]
	v_mfma_f32_16x16x32_bf16 v[36:39], v[154:157], v[178:181], v[36:39]
	v_mfma_f32_16x16x32_bf16 v[32:35], v[162:165], v[178:181], v[32:35]
	v_mfma_f32_16x16x32_bf16 v[20:23], v[154:157], v[206:209], v[20:23]
	v_mfma_f32_16x16x32_bf16 v[16:19], v[162:165], v[206:209], v[16:19]
	v_mfma_f32_16x16x32_bf16 v[8:11], v[154:157], v[218:221], v[8:11]
	v_mfma_f32_16x16x32_bf16 v[0:3], v[162:165], v[218:221], v[0:3]
	s_setprio 0
	s_barrier
	s_add_i32 s34, 0, 0x18000
	v_add_u32_e32 v112, s34, v250
	s_add_i32 s35, 0, 0x1c000
	ds_read_b128 v[134:137], v112
	ds_read_b128 v[138:141], v112 offset:1024
	ds_read_b128 v[142:145], v112 offset:2048
	ds_read_b128 v[146:149], v112 offset:3072
	v_add_u32_e32 v112, s35, v250
	ds_read_b128 v[150:153], v112
	ds_read_b128 v[154:157], v112 offset:1024
	ds_read_b128 v[158:161], v112 offset:2048
	ds_read_b128 v[162:165], v112 offset:3072
	s_add_u32 s6, s24, s49
	s_addc_u32 s7, s25, s37
	s_add_i32 m0, s36, 0x4000
	ds_read_b128 v[166:169], v240 offset:32768
	ds_read_b128 v[170:173], v240 offset:33792
	ds_read_b128 v[174:177], v240 offset:34816
	ds_read_b128 v[178:181], v240 offset:35840
	ds_read_b128 v[202:205], v240 offset:36864
	ds_read_b128 v[206:209], v240 offset:37888
	ds_read_b128 v[210:213], v240 offset:38912
	ds_read_b128 v[218:221], v240 offset:39936
	global_load_lds_dwordx4 v214, s[6:7]
	s_add_i32 m0, s36, 0x6000
	s_nop 0
	global_load_lds_dwordx4 v216, s[6:7]
	s_waitcnt vmcnt(8)
	s_waitcnt lgkmcnt(0)
	s_barrier
	s_setprio 1
	s_waitcnt lgkmcnt(0)
	v_mfma_f32_16x16x32_bf16 v[126:129], v[134:137], v[166:169], v[126:129]
	v_mfma_f32_16x16x32_bf16 v[122:125], v[142:145], v[166:169], v[122:125]
	v_mfma_f32_16x16x32_bf16 v[108:111], v[134:137], v[174:177], v[108:111]
	v_mfma_f32_16x16x32_bf16 v[104:107], v[142:145], v[174:177], v[104:107]
	v_mfma_f32_16x16x32_bf16 v[92:95], v[134:137], v[202:205], v[92:95]
	v_mfma_f32_16x16x32_bf16 v[88:91], v[142:145], v[202:205], v[88:91]
	v_mfma_f32_16x16x32_bf16 v[76:79], v[134:137], v[210:213], v[76:79]
	v_mfma_f32_16x16x32_bf16 v[72:75], v[142:145], v[210:213], v[72:75]
	v_mfma_f32_16x16x32_bf16 v[126:129], v[138:141], v[170:173], v[126:129]
	v_mfma_f32_16x16x32_bf16 v[122:125], v[146:149], v[170:173], v[122:125]
	v_mfma_f32_16x16x32_bf16 v[108:111], v[138:141], v[178:181], v[108:111]
	v_mfma_f32_16x16x32_bf16 v[104:107], v[146:149], v[178:181], v[104:107]
	v_mfma_f32_16x16x32_bf16 v[92:95], v[138:141], v[206:209], v[92:95]
	v_mfma_f32_16x16x32_bf16 v[88:91], v[146:149], v[206:209], v[88:91]
	v_mfma_f32_16x16x32_bf16 v[76:79], v[138:141], v[218:221], v[76:79]
	v_mfma_f32_16x16x32_bf16 v[72:75], v[146:149], v[218:221], v[72:75]
	s_setprio 0
	s_setprio 1
	v_mfma_f32_16x16x32_bf16 v[118:121], v[150:153], v[166:169], v[118:121]
	v_mfma_f32_16x16x32_bf16 v[114:117], v[158:161], v[166:169], v[114:117]
	v_mfma_f32_16x16x32_bf16 v[100:103], v[150:153], v[174:177], v[100:103]
	v_mfma_f32_16x16x32_bf16 v[96:99], v[158:161], v[174:177], v[96:99]
	v_mfma_f32_16x16x32_bf16 v[84:87], v[150:153], v[202:205], v[84:87]
	v_mfma_f32_16x16x32_bf16 v[80:83], v[158:161], v[202:205], v[80:83]
	v_mfma_f32_16x16x32_bf16 v[68:71], v[150:153], v[210:213], v[68:71]
	v_mfma_f32_16x16x32_bf16 v[64:67], v[158:161], v[210:213], v[64:67]
	v_mfma_f32_16x16x32_bf16 v[118:121], v[154:157], v[170:173], v[118:121]
	v_mfma_f32_16x16x32_bf16 v[114:117], v[162:165], v[170:173], v[114:117]
	v_mfma_f32_16x16x32_bf16 v[100:103], v[154:157], v[178:181], v[100:103]
	v_mfma_f32_16x16x32_bf16 v[96:99], v[162:165], v[178:181], v[96:99]
	v_mfma_f32_16x16x32_bf16 v[84:87], v[154:157], v[206:209], v[84:87]
	v_mfma_f32_16x16x32_bf16 v[80:83], v[162:165], v[206:209], v[80:83]
	v_mfma_f32_16x16x32_bf16 v[68:71], v[154:157], v[218:221], v[68:71]
	v_mfma_f32_16x16x32_bf16 v[64:67], v[162:165], v[218:221], v[64:67]
	s_setprio 0
	s_barrier
	s_add_i32 s6, s34, s20
	v_lshl_add_u64 v[214:215], v[224:225], 0, s[42:43]
	s_mov_b32 m0, s6
	ds_read_b128 v[166:169], v240 offset:49152
	ds_read_b128 v[170:173], v240 offset:50176
	ds_read_b128 v[174:177], v240 offset:51200
	ds_read_b128 v[178:181], v240 offset:52224
	ds_read_b128 v[202:205], v240 offset:53248
	ds_read_b128 v[206:209], v240 offset:54272
	ds_read_b128 v[210:213], v240 offset:55296
	ds_read_b128 v[218:221], v240 offset:56320
	global_load_lds_dwordx4 v[214:215], off
	v_lshl_add_u64 v[214:215], v[226:227], 0, s[42:43]
	s_add_i32 m0, s6, 0x2000
	s_add_i32 s6, s35, s20
	global_load_lds_dwordx4 v[214:215], off
	v_lshl_add_u64 v[214:215], v[228:229], 0, s[42:43]
	s_mov_b32 m0, s6
	s_nop 0
	global_load_lds_dwordx4 v[214:215], off
	v_lshl_add_u64 v[214:215], v[230:231], 0, s[42:43]
	s_add_i32 m0, s6, 0x2000
	s_nop 0
	global_load_lds_dwordx4 v[214:215], off
	v_lshl_add_u64 v[214:215], v[222:223], 0, s[42:43]
	s_add_i32 m0, s36, 0x8000
	s_nop 0
	global_load_lds_dwordx4 v[214:215], off
	v_lshl_add_u64 v[214:215], v[232:233], 0, s[42:43]
	s_add_i32 m0, s36, 0xa000
	s_nop 0
	global_load_lds_dwordx4 v[214:215], off
	s_waitcnt vmcnt(8)
	s_waitcnt lgkmcnt(0)
	s_barrier
	s_setprio 1
	s_waitcnt lgkmcnt(0)
	v_mfma_f32_16x16x32_bf16 v[60:63], v[134:137], v[166:169], v[60:63]
	v_mfma_f32_16x16x32_bf16 v[56:59], v[142:145], v[166:169], v[56:59]
	v_mfma_f32_16x16x32_bf16 v[44:47], v[134:137], v[174:177], v[44:47]
	v_mfma_f32_16x16x32_bf16 v[40:43], v[142:145], v[174:177], v[40:43]
	v_mfma_f32_16x16x32_bf16 v[28:31], v[134:137], v[202:205], v[28:31]
	v_mfma_f32_16x16x32_bf16 v[24:27], v[142:145], v[202:205], v[24:27]
	v_mfma_f32_16x16x32_bf16 v[12:15], v[134:137], v[210:213], v[12:15]
	v_mfma_f32_16x16x32_bf16 v[4:7], v[142:145], v[210:213], v[4:7]
	v_mfma_f32_16x16x32_bf16 v[60:63], v[138:141], v[170:173], v[60:63]
	v_mfma_f32_16x16x32_bf16 v[56:59], v[146:149], v[170:173], v[56:59]
	v_mfma_f32_16x16x32_bf16 v[44:47], v[138:141], v[178:181], v[44:47]
	v_mfma_f32_16x16x32_bf16 v[40:43], v[146:149], v[178:181], v[40:43]
	v_mfma_f32_16x16x32_bf16 v[28:31], v[138:141], v[206:209], v[28:31]
	v_mfma_f32_16x16x32_bf16 v[24:27], v[146:149], v[206:209], v[24:27]
	v_mfma_f32_16x16x32_bf16 v[12:15], v[138:141], v[218:221], v[12:15]
	v_mfma_f32_16x16x32_bf16 v[4:7], v[146:149], v[218:221], v[4:7]
	s_setprio 0
	s_setprio 1
	v_mfma_f32_16x16x32_bf16 v[52:55], v[150:153], v[166:169], v[52:55]
	v_mfma_f32_16x16x32_bf16 v[48:51], v[158:161], v[166:169], v[48:51]
	v_mfma_f32_16x16x32_bf16 v[36:39], v[150:153], v[174:177], v[36:39]
	v_mfma_f32_16x16x32_bf16 v[32:35], v[158:161], v[174:177], v[32:35]
	v_mfma_f32_16x16x32_bf16 v[20:23], v[150:153], v[202:205], v[20:23]
	v_mfma_f32_16x16x32_bf16 v[16:19], v[158:161], v[202:205], v[16:19]
	v_mfma_f32_16x16x32_bf16 v[8:11], v[150:153], v[210:213], v[8:11]
	v_mfma_f32_16x16x32_bf16 v[0:3], v[158:161], v[210:213], v[0:3]
	v_mfma_f32_16x16x32_bf16 v[52:55], v[154:157], v[170:173], v[52:55]
	v_mfma_f32_16x16x32_bf16 v[48:51], v[162:165], v[170:173], v[48:51]
	v_mfma_f32_16x16x32_bf16 v[36:39], v[154:157], v[178:181], v[36:39]
	v_mfma_f32_16x16x32_bf16 v[32:35], v[162:165], v[178:181], v[32:35]
	v_mfma_f32_16x16x32_bf16 v[20:23], v[154:157], v[206:209], v[20:23]
	v_mfma_f32_16x16x32_bf16 v[16:19], v[162:165], v[206:209], v[16:19]
	v_mfma_f32_16x16x32_bf16 v[8:11], v[154:157], v[218:221], v[8:11]
	v_mfma_f32_16x16x32_bf16 v[0:3], v[162:165], v[218:221], v[0:3]
	s_setprio 0
	s_barrier
	s_add_i32 s6, s33, 2
	s_add_u32 s22, s22, 0x100
	s_addc_u32 s23, s23, 0
	v_lshl_add_u64 v[130:131], v[130:131], 0, s[46:47]
	s_cmp_ge_u32 s33, s3
	v_lshl_add_u64 v[132:133], v[132:133], 0, s[46:47]
	s_cbranch_scc1 .LBB0_422
	s_mov_b32 s33, s6
	s_branch .LBB0_288

.LBB0_985:
	s_mov_b32 s6, s94
	v_mov_b32_e32 v3, 0
	v_writelane_b32 v254, s6, 36
	s_lshr_b32 s3, s14, 6
	s_xor_b64 s[4:5], s[16:17], -1
	s_mov_b32 s39, s68
	s_mov_b64 s[16:17], -1
	v_writelane_b32 v254, s7, 37
	s_mov_b32 s74, s95
	s_andn2_b64 vcc, exec, s[12:13]
	s_cbranch_vccnz .LBB0_987
	s_branch .LBB0_988
